# W_up/W_out f32->bf16 transposes moved from P0 into GEMM1 main loop (batched row loads, 2 per tile)
# speedup vs baseline: 1.0074x; 1.0074x over previous
; __device__ __forceinline__ void phase_prologue(Ctx& X) {
;     ...
;     for (int it = X.gw; it < NIT; it += X.NGW) {
;         int r = it;
;         if (r < I_IN) { transpose_item(X.w_in, D, INW, win, scr, r, X.lane); continue; } r -= I_IN;
;         if (r < I_OUT) { transpose_item(X.w_out, D, D, wout, scr, r, X.lane); continue; } r -= I_OUT;
;         if (r < I_UP) { transpose_item(X.w_up, D, UPW, wup, scr, r, X.lane, true); continue; } r -= I_UP;
;         transpose_item(X.w_down, DFF, D, wdn, scr, r, X.lane);
;     }
.LBB0_29:
	s_add_i32 s21, s21, s50
	s_add_i32 s3, s3, s50
	s_add_i32 s4, s4, s12
	s_add_i32 s13, s13, s50
	s_add_i32 s14, s14, s12
	s_add_i32 s15, s15, s50
	s_add_i32 s6, s6, s12
	s_add_i32 s18, s18, s12
	s_cmp_lg_u32 s94, 0x100
	s_cbranch_scc1 .Lp0_nj
	s_cmpk_lt_i32 s21, 0xe00
	s_cbranch_scc1 .Lp0_nj
	s_sub_i32 s0, s21, s50
	s_cmpk_lt_i32 s0, 0xe00
	s_cbranch_scc0 .Lp0_nj
	s_addk_i32 s21, 0x1a00
	s_addk_i32 s3, 0x1a00
	s_addk_i32 s13, 0x1a00
	s_addk_i32 s15, 0x1a00
	s_add_i32 s4, s4, 0x68000
	s_add_i32 s14, s14, 0x68000
	s_add_i32 s6, s6, 0x68000
	s_add_i32 s18, s18, 0x68000
.Lp0_nj:
	s_cmpk_lt_i32 s21, 0x3300
	s_cbranch_scc0 .LBB0_50

; #define PG8_STAGE(bufoff, gbase, voff) do { _Pragma("unroll") for (int _i = 0; _i < 2; ++_i) \
;         __builtin_amdgcn_global_load_lds((const unsigned*)((const char*)(gbase) + (voff)[_i]), (LAS unsigned*)(lds + (bufoff) + ldsw + _i * 8192), 16, 0, 0); } while (0)
; #define PG8_WAIT_V(n) asm volatile("s_waitcnt vmcnt(" #n ")" ::: "memory")
; #define PG8_BAR __builtin_amdgcn_s_barrier()
; template <class Epi, class Sched>
; __device__ __forceinline__ void gemm_phase(LAS unsigned char* lds, const Gemm g, const Sched& S, const Epi& E) {
;     const int tid = threadIdx.x, wid = __builtin_amdgcn_readfirstlane(tid >> 6), lane = tid & 63, wr = wid >> 2, wc = wid & 3, fr = lane & 15, fq = lane >> 4;
;     const int K = g.K, nt = K / BK, lda = g.lda;
;     unsigned voffA[2], voffB[2];
; #pragma unroll
;     for (int i = 0; i < 2; ++i) { int R, C; stage_rc(tid * 16 + i * 8192, R, C); const int Rb = Epi::PERM ? ((R & ~31) + perm32(R & 31)) : R;
;         voffA[i] = (unsigned)(R * lda + C) * 2u; voffB[i] = (unsigned)(Rb * K + C) * 2u; }
;     const size_t kstep = (size_t)(BK * 2);
;     const size_t hstepA = (size_t)HALF * lda * 2, hstepB = (size_t)HALF * K * 2;
;     const size_t tstepA = 2 * hstepA, tstepB = 2 * hstepB;
;     const unsigned ldsw = (unsigned)wid * 1024u;
;     const int aoff = lds_byte(wr * 64 + fr, fq * 8), boff = lds_byte(wc * 32 + fr, fq * 8);
;     ...
;     Unit cur, nxt; int ui = 0;
;     if (!S.next(0, cur)) return;
;     f32x4 acc[2][2][4][2];
; #pragma unroll
;     for (int a = 0; a < 2; ++a)
; #pragma unroll
;         for (int b = 0; b < 2; ++b)
; #pragma unroll
;             for (int m = 0; m < 4; ++m)
; #pragma unroll
;                 for (int n = 0; n < 2; ++n) acc[a][b][m][n] = (f32x4){0.f, 0.f, 0.f, 0.f};
;     bf16x8 At[4][2], B0[2][2], B1[2][2];
;     const char* cA = (const char*)g.A + (size_t)cur.pm * tstepA; const char* cB = (const char*)g.Bt + (size_t)cur.pn * tstepB;
;     PG8_STAGE(PG8_SB(0, 0), cB, voffB); PG8_STAGE(PG8_SB(0, 1), cB + hstepB, voffB); PG8_STAGE(PG8_SA(0, 0), cA, voffA); PG8_STAGE(PG8_SA(0, 1), cA + hstepA, voffA);
;     if (wr == 1) PG8_BAR;
;     PG8_WAIT_V(2); PG8_BAR;
;     PG8_STAGE(PG8_SB(1, 0), cB + kstep, voffB); PG8_STAGE(PG8_SA(1, 0), cA + kstep, voffA); PG8_STAGE(PG8_SB(1, 1), cB + hstepB + kstep, voffB);
;     PG8_WAIT_V(6); PG8_BAR;
.LBB0_172:
	s_mov_b64 s[18:19], 0x80
	s_and_b32 s7, s1, 3
	s_add_i32 m0, s53, 0x18000
	v_lshl_add_u64 v[6:7], v[6:7], 0, s[18:19]
	s_lshl_b32 s1, s0, 13
	s_lshl_b32 s11, s7, 12
	s_waitcnt vmcnt(2)
	s_barrier
	global_load_lds_dwordx4 v[6:7], off
	v_lshl_add_u64 v[4:5], v[4:5], 0, s[18:19]
	s_add_i32 m0, s53, 0x1a000
	s_add_i32 s58, s53, 0x8000
	s_add_i32 s59, s53, 0xa000
	global_load_lds_dwordx4 v[4:5], off
	v_lshl_add_u64 v[0:1], v[0:1], 0, s[18:19]
	s_mov_b32 m0, s58
	s_add_u32 s4, s12, 0x80080
	global_load_lds_dwordx4 v[0:1], off
	v_lshl_add_u64 v[0:1], v[2:3], 0, s[18:19]
	s_mov_b32 m0, s59
	s_addc_u32 s5, s13, 0
	global_load_lds_dwordx4 v[0:1], off
	s_add_i32 m0, s53, 0x1c000
	v_lshl_add_u64 v[0:1], s[4:5], 0, v[130:131]
	global_load_lds_dwordx4 v[0:1], off
	v_lshl_add_u64 v[0:1], s[4:5], 0, v[134:135]
	s_add_i32 m0, s53, 0x1e000
	v_lshlrev_b32_e32 v4, 2, v209
	global_load_lds_dwordx4 v[0:1], off
	v_bfe_u32 v1, v209, 4, 2
	v_and_b32_e32 v0, 15, v209
	v_lshlrev_b32_e32 v3, 4, v1
	v_lshl_or_b32 v160, s0, 6, v0
	v_lshl_or_b32 v0, v0, 6, v3
	v_and_b32_e32 v4, 32, v4
	v_bitop3_b32 v5, v0, s1, v4 bitop3:0xde
	v_lshlrev_b32_e32 v0, 6, v209
	s_movk_i32 s0, 0x3c0
	v_and_or_b32 v0, v0, s0, v3
	v_bitop3_b32 v161, s11, v0, v4 bitop3:0xf6
	s_cmpk_lt_u32 s2, 0x100
	v_readlane_b32 s22, v245, 0
	v_lshlrev_b32_e32 v0, 1, v209
	s_cselect_b64 s[20:21], -1, 0
	s_cmp_eq_u32 s7, 0
	v_readlane_b32 s23, v245, 1
	v_and_b32_e32 v136, 32, v0
	v_lshlrev_b32_e32 v2, 3, v1
	s_cselect_b64 s[4:5], -1, 0
	v_cmp_gt_u32_e64 s[0:1], 2, v1
	s_ashr_i32 s62, s22, 31
	v_lshl_add_u64 v[0:1], s[90:91], 0, v[136:137]
	s_mov_b64 s[22:23], 0x4300000
	v_lshl_add_u64 v[138:139], v[0:1], 0, s[22:23]
	v_lshlrev_b32_e32 v0, 9, v209
	v_and_b32_e32 v0, 0x70000, v0
	v_lshlrev_b32_e32 v1, 12, v10
	v_or3_b32 v0, v8, v0, v1
	v_readlane_b32 s68, v245, 31
	v_add_u32_e32 v140, v0, v9
	v_lshlrev_b32_e32 v0, 5, v11
	s_ashr_i32 s60, s94, 31
	v_readlane_b32 s82, v245, 45
	v_and_b32_e32 v0, 0xf0000, v0
	s_waitcnt vmcnt(6)
	v_readlane_b32 s83, v245, 46
	s_add_u32 s22, s82, 0x1000
	v_or3_b32 v0, v8, v0, v1
	s_addc_u32 s23, s83, 0
	v_add_u32_e32 v142, v0, v9
	s_add_i32 s64, 0, 0x10000
	s_add_i32 s65, 0, 0x14000
	v_mbcnt_lo_u32_b32 v0, -1, 0
	s_mov_b32 s61, s94
	v_lshl_or_b32 v162, s7, 5, v2
	v_mov_b32_e32 v141, v137
	v_mov_b32_e32 v143, v137
	v_mov_b64_e32 v[144:145], 0x700
	v_mov_b64_e32 v[146:147], 0x6ff
	s_movk_i32 s63, 0xe1
	v_add_u32_e32 v163, s64, v161
	v_add_u32_e32 v164, s65, v161
	v_add_u32_e32 v165, 0, v5
	s_mov_b32 s66, 0x800000
	s_mov_b32 s67, 0x3f317217
	s_mov_b32 s68, 0x7f800000
	s_mov_b32 s24, 0x3db504f3
	s_mov_b64 s[26:27], 0x1200
	s_xor_b64 s[28:29], s[4:5], -1
	v_mov_b32_e32 v166, 0x41b17218
	v_mbcnt_hi_u32_b32 v167, -1, v0
	s_barrier
	v_readlane_b32 s69, v245, 32
	v_readlane_b32 s70, v245, 33
	v_readlane_b32 s71, v245, 34
	v_readlane_b32 s72, v245, 35
	v_readlane_b32 s73, v245, 36
	v_readlane_b32 s74, v245, 37
	v_readlane_b32 s75, v245, 38
	v_readlane_b32 s76, v245, 39
	v_readlane_b32 s77, v245, 40
	v_readlane_b32 s78, v245, 41
	v_readlane_b32 s79, v245, 42
	v_readlane_b32 s80, v245, 43
	v_readlane_b32 s81, v245, 44
	v_lshlrev_b32_e32 v240, 3, v208
	s_branch .LBB0_175

;     __host__ __device__ bool next(int i, Unit& u) const {
;         const long L = (long)i * G + c; if (L >= nwg) return false;
;         int wgid = (int)L; { const int q = nwg / NXCD, r = nwg % NXCD, xcd = wgid % NXCD, off = wgid / NXCD; wgid = (xcd < r ? xcd * (q + 1) : r * (q + 1) + (xcd - r) * q) + off; }
;         const int nig = WGM * nN, gid = wgid / nig, fm = gid * WGM, gsz = (nM - fm) < WGM ? (nM - fm) : WGM;
;         u.pm = fm + ((wgid % nig) % gsz); u.pn = (wgid % nig) / gsz; return true;
; __device__ __forceinline__ void transpose_item(const float* __restrict__ W, int K, int N, bf16_t* __restrict__ WT, LAS float* scr, int item, int lane, bool upmap = false) {
;     const int nblk = N >> 6, kb = item / nblk, nb = item - kb * nblk, k0 = kb * 64, n0s = nb * 64;
;     const int n0 = !upmap ? n0s : (n0s < DFF ? 256 * (n0s >> 7) + (n0s & 127) : 256 * ((n0s - DFF) >> 7) + 128 + ((n0s - DFF) & 127));
;     const float* src = W + (size_t)k0 * N + n0s + lane;
.LBB0_175:
	s_add_i32 s57, s57, 1
	s_add_i32 s101, s57, -1
	s_lshl_b32 s101, s101, 11
	s_add_i32 s101, s101, s96
	s_cmp_lg_u32 s94, 0x100
	s_cselect_b32 s101, 0x4000, s101
	s_cmpk_lt_u32 s101, 0x3400
	s_cselect_b32 s101, s101, 0
	s_cmpk_lt_u32 s101, 0x2c00
	s_cbranch_scc0 .Lwc_src_out
	v_readlane_b32 s98, v245, 11
	v_readlane_b32 s99, v245, 12
	s_and_b32 s32, s101, 0x7f
	s_mul_i32 s32, s32, 0xb0000
	s_lshr_b32 s100, s101, 7
	s_lshl_b32 s100, s100, 9
	s_add_i32 s32, s32, s100
	s_mov_b32 s100, 0xb000
	s_branch .Lwc_src_j
.Lwc_src_out:
	s_sub_i32 s101, s101, 0x2c00
	v_readlane_b32 s98, v245, 7
	v_readlane_b32 s99, v245, 8
	s_and_b32 s32, s101, 0x7f
	s_lshl_b32 s32, s32, 17
	s_lshr_b32 s100, s101, 7
	s_lshl_b32 s100, s100, 9
	s_add_i32 s32, s32, s100
	s_mov_b32 s100, 0x2000
.Lwc_src_j:
	s_add_u32 s98, s98, s32
	s_addc_u32 s99, s99, 0
	s_mul_i32 s2, s57, s60
	s_mul_hi_u32 s4, s57, s61
	s_add_i32 s4, s4, s2
	s_mul_i32 s2, s57, s61
	v_readlane_b32 s36, v245, 0
	v_readlane_b32 s37, v245, 1
	s_add_u32 s36, s2, s36
	s_addc_u32 s37, s4, s62
	v_cmp_gt_i64_e32 vcc, s[36:37], v[146:147]
	v_cmp_lt_i64_e64 s[4:5], s[36:37], v[144:145]
	s_cbranch_vccnz .LBB0_177
	s_ashr_i32 s2, s36, 31
	s_lshr_b32 s2, s2, 29
	s_add_i32 s2, s36, s2
	s_ashr_i32 s7, s2, 3
	s_and_b32 s2, s2, -8
	s_sub_i32 s2, s36, s2
	s_cmp_lt_i32 s2, 0
	s_cselect_b32 s11, s63, 0xe0
	s_mul_i32 s2, s2, s11
	s_add_i32 s2, s2, s7
	s_mul_hi_i32 s7, s2, 0x92492493
	s_add_i32 s7, s7, s2
	s_lshr_b32 s11, s7, 31
	s_ashr_i32 s7, s7, 6
	s_add_i32 s7, s7, s11
	s_lshl_b32 s11, s7, 2
	s_sub_i32 s30, 64, s11
	s_min_i32 s31, s30, 4
	s_abs_i32 s30, s31
	v_cvt_f32_u32_e32 v0, s30
	s_sub_i32 s34, 0, s30
	s_mulk_i32 s7, 0x70
	s_sub_i32 s2, s2, s7
	v_rcp_iflag_f32_e32 v0, v0
	s_abs_i32 s7, s2
	s_xor_b32 s33, s2, s31
	s_ashr_i32 s33, s33, 31
	v_mul_f32_e32 v0, 0x4f7ffffe, v0
	v_cvt_u32_f32_e32 v0, v0
	s_nop 0
	v_readfirstlane_b32 s35, v0
	s_mul_i32 s34, s34, s35
	s_mul_hi_u32 s34, s35, s34
	s_add_i32 s35, s35, s34
	s_mul_hi_u32 s34, s7, s35
	s_mul_i32 s35, s34, s30
	s_sub_i32 s7, s7, s35
	s_add_i32 s36, s34, 1
	s_sub_i32 s35, s7, s30
	s_cmp_ge_u32 s7, s30
	s_cselect_b32 s34, s36, s34
	s_cselect_b32 s7, s35, s7
	s_add_i32 s35, s34, 1
	s_cmp_ge_u32 s7, s30
	s_cselect_b32 s7, s35, s34
	s_xor_b32 s7, s7, s33
	s_sub_i32 s30, s7, s33
	s_mul_i32 s7, s30, s31
	s_sub_i32 s2, s2, s7
	s_add_i32 s34, s11, s2

; #define PG8_STAGE(bufoff, gbase, voff) do { _Pragma("unroll") for (int _i = 0; _i < 2; ++_i) \
;         __builtin_amdgcn_global_load_lds((const unsigned*)((const char*)(gbase) + (voff)[_i]), (LAS unsigned*)(lds + (bufoff) + ldsw + _i * 8192), 16, 0, 0); } while (0)
; #define PG8_LDA(dst, b, h) do { _Pragma("unroll") for (int m = 0; m < 4; ++m) _Pragma("unroll") for (int k = 0; k < 2; ++k) dst[m][k] = *(const LAS bf16x8*)(lds + PG8_SA(b, h) + aoff + m * 2048 + k * 1024); } while (0)
; #define PG8_LDB(dst, b, h) do { _Pragma("unroll") for (int n = 0; n < 2; ++n) _Pragma("unroll") for (int k = 0; k < 2; ++k) dst[n][k] = *(const LAS bf16x8*)(lds + PG8_SB(b, h) + boff + n * 2048 + k * 1024); } while (0)
; #define PG8_MMA(ai, bj, At, Bt) do { __builtin_amdgcn_s_setprio(1); _Pragma("unroll") for (int m = 0; m < 4; ++m) _Pragma("unroll") for (int n = 0; n < 2; ++n) _Pragma("unroll") for (int k = 0; k < 2; ++k) \
;         acc[ai][bj][m][n] = __builtin_amdgcn_mfma_f32_16x16x32_bf16(Bt[n][k], At[m][k], acc[ai][bj][m][n], 0, 0, 0); __builtin_amdgcn_s_setprio(0); } while (0)
; #define PG8_WAIT_V(n) asm volatile("s_waitcnt vmcnt(" #n ")" ::: "memory")
; #define PG8_WAIT_L(n) asm volatile("s_waitcnt lgkmcnt(" #n ")" ::: "memory")
; #define PG8_BAR __builtin_amdgcn_s_barrier()
; #define PG8_SCHED __builtin_amdgcn_sched_barrier(0)
; template <class Epi, class Sched>
; __device__ __forceinline__ void gemm_phase(LAS unsigned char* lds, const Gemm g, const Sched& S, const Epi& E) {
;     ...
;         for (int t = 0; t < nt; t += 2) {
;             const bool last = (t == nt - 2);
;             const char* a1 = cA + (size_t)(t + 1) * kstep;
;             const char* a2 = last ? nA : cA + (size_t)(t + 2) * kstep; const char* b2 = last ? nB : cB + (size_t)(t + 2) * kstep;
;             const char* a3 = a2 + kstep; const char* b3 = b2 + kstep;
;             PG8_LDB(B0, 0, 0); PG8_LDB(B1, 0, 1); PG8_SCHED; PG8_LDA(At, 0, 0); PG8_STAGE(PG8_SA(1, 1), a1 + hstepA, voffA);
;             PG8_WAIT_V(8); PG8_WAIT_L(0); PG8_BAR; PG8_MMA(0, 0, At, B0); PG8_MMA(0, 1, At, B1); PG8_BAR; PG8_SCHED;
;             PG8_LDA(At, 0, 1); PG8_STAGE(PG8_SB(0, 0), b2, voffB); PG8_STAGE(PG8_SB(0, 1), b2 + hstepB, voffB); PG8_STAGE(PG8_SA(0, 0), a2, voffA);
;             PG8_WAIT_V(8); PG8_WAIT_L(0); PG8_BAR; PG8_MMA(1, 0, At, B0); PG8_MMA(1, 1, At, B1); PG8_BAR; PG8_SCHED;
.LBB0_178:
	ds_read_b128 v[148:151], v163
	ds_read_b128 v[152:155], v163 offset:1024
	ds_read_b128 v[156:159], v163 offset:2048
	ds_read_b128 v[168:171], v163 offset:3072
	ds_read_b128 v[172:175], v164
	ds_read_b128 v[176:179], v164 offset:1024
	ds_read_b128 v[180:183], v164 offset:2048
	ds_read_b128 v[184:187], v164 offset:3072
	s_add_u32 s2, s8, 0xfff80080
	s_addc_u32 s12, s9, -1
	s_cmp_eq_u32 s43, 28
	s_cselect_b32 s41, s7, s12
	s_cselect_b32 s40, s11, s2
	s_cselect_b32 s13, s31, s42
	s_cselect_b32 s12, s33, s35
	v_lshl_add_u64 v[222:223], s[8:9], 0, v[140:141]
	s_add_i32 m0, s53, 0xc000
	ds_read_b128 v[188:191], v165
	ds_read_b128 v[192:195], v165 offset:1024
	ds_read_b128 v[196:199], v165 offset:2048
	ds_read_b128 v[200:203], v165 offset:3072
	ds_read_b128 v[204:207], v165 offset:4096
	ds_read_b128 v[210:213], v165 offset:5120
	ds_read_b128 v[214:217], v165 offset:6144
	ds_read_b128 v[218:221], v165 offset:7168
	global_load_lds_dwordx4 v[222:223], off
	v_lshl_add_u64 v[222:223], s[8:9], 0, v[142:143]
	s_add_i32 m0, s53, 0xe000
	s_nop 0
	global_load_lds_dwordx4 v[222:223], off
	global_load_dwordx2 v[232:233], v240, s[98:99] nt
	s_add_u32 s98, s98, s100
	s_addc_u32 s99, s99, 0
	global_load_dwordx2 v[234:235], v240, s[98:99] nt
	s_add_u32 s98, s98, s100
	s_addc_u32 s99, s99, 0
	global_load_dwordx2 v[236:237], v240, s[98:99] nt
	s_add_u32 s98, s98, s100
	s_addc_u32 s99, s99, 0
	global_load_dwordx2 v[238:239], v240, s[98:99] nt
	s_add_u32 s98, s98, s100
	s_addc_u32 s99, s99, 0
	global_load_dwordx2 a[0:1], v240, s[98:99] nt
	s_add_u32 s98, s98, s100
	s_addc_u32 s99, s99, 0
	global_load_dwordx2 a[2:3], v240, s[98:99] nt
	s_add_u32 s98, s98, s100
	s_addc_u32 s99, s99, 0
	global_load_dwordx2 a[4:5], v240, s[98:99] nt
	s_add_u32 s98, s98, s100
	s_addc_u32 s99, s99, 0
	global_load_dwordx2 a[6:7], v240, s[98:99] nt
	s_add_u32 s98, s98, s100
	s_addc_u32 s99, s99, 0
	s_waitcnt vmcnt(16)
	s_waitcnt lgkmcnt(0)
	s_barrier
	s_setprio 1
	s_waitcnt lgkmcnt(0)
	v_mfma_f32_16x16x32_bf16 v[124:127], v[148:151], v[188:191], v[124:127]
	v_mfma_f32_16x16x32_bf16 v[120:123], v[156:159], v[188:191], v[120:123]
	v_mfma_f32_16x16x32_bf16 v[116:119], v[148:151], v[196:199], v[116:119]
	v_mfma_f32_16x16x32_bf16 v[112:115], v[156:159], v[196:199], v[112:115]
	v_mfma_f32_16x16x32_bf16 v[108:111], v[148:151], v[204:207], v[108:111]
	v_mfma_f32_16x16x32_bf16 v[104:107], v[156:159], v[204:207], v[104:107]
	v_mfma_f32_16x16x32_bf16 v[100:103], v[148:151], v[214:217], v[100:103]
	v_mfma_f32_16x16x32_bf16 v[96:99], v[156:159], v[214:217], v[96:99]
	v_mfma_f32_16x16x32_bf16 v[124:127], v[152:155], v[192:195], v[124:127]
	v_mfma_f32_16x16x32_bf16 v[120:123], v[168:171], v[192:195], v[120:123]
	v_mfma_f32_16x16x32_bf16 v[116:119], v[152:155], v[200:203], v[116:119]
	v_mfma_f32_16x16x32_bf16 v[112:115], v[168:171], v[200:203], v[112:115]
	v_mfma_f32_16x16x32_bf16 v[108:111], v[152:155], v[210:213], v[108:111]
	v_mfma_f32_16x16x32_bf16 v[104:107], v[168:171], v[210:213], v[104:107]
	v_mfma_f32_16x16x32_bf16 v[100:103], v[152:155], v[218:221], v[100:103]
	v_mfma_f32_16x16x32_bf16 v[96:99], v[168:171], v[218:221], v[96:99]
	s_setprio 0
	s_setprio 1
	v_mfma_f32_16x16x32_bf16 v[60:63], v[172:175], v[188:191], v[60:63]
	v_mfma_f32_16x16x32_bf16 v[56:59], v[180:183], v[188:191], v[56:59]
	v_mfma_f32_16x16x32_bf16 v[52:55], v[172:175], v[196:199], v[52:55]
	v_mfma_f32_16x16x32_bf16 v[48:51], v[180:183], v[196:199], v[48:51]
	v_mfma_f32_16x16x32_bf16 v[44:47], v[172:175], v[204:207], v[44:47]
	v_mfma_f32_16x16x32_bf16 v[40:43], v[180:183], v[204:207], v[40:43]
	v_mfma_f32_16x16x32_bf16 v[36:39], v[172:175], v[214:217], v[36:39]
	v_mfma_f32_16x16x32_bf16 v[32:35], v[180:183], v[214:217], v[32:35]
	v_mfma_f32_16x16x32_bf16 v[60:63], v[176:179], v[192:195], v[60:63]
	v_mfma_f32_16x16x32_bf16 v[56:59], v[184:187], v[192:195], v[56:59]
	v_mfma_f32_16x16x32_bf16 v[52:55], v[176:179], v[200:203], v[52:55]
	v_mfma_f32_16x16x32_bf16 v[48:51], v[184:187], v[200:203], v[48:51]
	v_mfma_f32_16x16x32_bf16 v[44:47], v[176:179], v[210:213], v[44:47]
	v_mfma_f32_16x16x32_bf16 v[40:43], v[184:187], v[210:213], v[40:43]
	v_mfma_f32_16x16x32_bf16 v[36:39], v[176:179], v[218:221], v[36:39]
	v_mfma_f32_16x16x32_bf16 v[32:35], v[184:187], v[218:221], v[32:35]
	s_setprio 0
	s_barrier
	s_add_i32 s2, s64, s52
	v_lshl_add_u64 v[222:223], s[12:13], 0, v[130:131]
	s_mov_b32 m0, s2
	ds_read_b128 v[188:191], v165 offset:16384
	ds_read_b128 v[192:195], v165 offset:17408
	ds_read_b128 v[196:199], v165 offset:18432
	ds_read_b128 v[200:203], v165 offset:19456
	ds_read_b128 v[204:207], v165 offset:20480
	ds_read_b128 v[210:213], v165 offset:21504
	ds_read_b128 v[214:217], v165 offset:22528
	ds_read_b128 v[218:221], v165 offset:23552
	global_load_lds_dwordx4 v[222:223], off
	s_add_i32 m0, s2, 0x2000
	s_add_u32 s44, s12, 0x80000
	v_lshl_add_u64 v[224:225], s[12:13], 0, v[134:135]
	s_addc_u32 s45, s13, 0
	s_add_i32 s2, s65, s52
	global_load_lds_dwordx4 v[224:225], off
	v_lshl_add_u64 v[226:227], s[44:45], 0, v[130:131]
	s_mov_b32 m0, s2
	v_lshl_add_u64 v[228:229], s[40:41], 0, v[132:133]
	global_load_lds_dwordx4 v[226:227], off
	v_lshl_add_u64 v[226:227], s[44:45], 0, v[134:135]
	s_add_i32 m0, s2, 0x2000
	s_nop 0
	global_load_lds_dwordx4 v[226:227], off
	v_lshl_add_u64 v[226:227], s[40:41], 0, v[128:129]
	s_mov_b32 m0, s53
	s_nop 0
	global_load_lds_dwordx4 v[226:227], off
	s_mov_b32 m0, s54
	s_nop 0
	global_load_lds_dwordx4 v[228:229], off
	s_waitcnt vmcnt(16)
	s_waitcnt lgkmcnt(0)
	s_barrier
; #define PG8_STAGE(bufoff, gbase, voff) do { _Pragma("unroll") for (int _i = 0; _i < 2; ++_i) \
;         __builtin_amdgcn_global_load_lds((const unsigned*)((const char*)(gbase) + (voff)[_i]), (LAS unsigned*)(lds + (bufoff) + ldsw + _i * 8192), 16, 0, 0); } while (0)
; #define PG8_LDA(dst, b, h) do { _Pragma("unroll") for (int m = 0; m < 4; ++m) _Pragma("unroll") for (int k = 0; k < 2; ++k) dst[m][k] = *(const LAS bf16x8*)(lds + PG8_SA(b, h) + aoff + m * 2048 + k * 1024); } while (0)
; #define PG8_LDB(dst, b, h) do { _Pragma("unroll") for (int n = 0; n < 2; ++n) _Pragma("unroll") for (int k = 0; k < 2; ++k) dst[n][k] = *(const LAS bf16x8*)(lds + PG8_SB(b, h) + boff + n * 2048 + k * 1024); } while (0)
; #define PG8_MMA(ai, bj, At, Bt) do { __builtin_amdgcn_s_setprio(1); _Pragma("unroll") for (int m = 0; m < 4; ++m) _Pragma("unroll") for (int n = 0; n < 2; ++n) _Pragma("unroll") for (int k = 0; k < 2; ++k) \
;         acc[ai][bj][m][n] = __builtin_amdgcn_mfma_f32_16x16x32_bf16(Bt[n][k], At[m][k], acc[ai][bj][m][n], 0, 0, 0); __builtin_amdgcn_s_setprio(0); } while (0)
; #define PG8_WAIT_V(n) asm volatile("s_waitcnt vmcnt(" #n ")" ::: "memory")
; #define PG8_WAIT_L(n) asm volatile("s_waitcnt lgkmcnt(" #n ")" ::: "memory")
; #define PG8_BAR __builtin_amdgcn_s_barrier()
; #define PG8_SCHED __builtin_amdgcn_sched_barrier(0)
; template <class Epi, class Sched>
; __device__ __forceinline__ void gemm_phase(LAS unsigned char* lds, const Gemm g, const Sched& S, const Epi& E) {
;     ...
;             PG8_WAIT_V(8); PG8_WAIT_L(0); PG8_BAR; PG8_MMA(1, 0, At, B0); PG8_MMA(1, 1, At, B1); PG8_BAR; PG8_SCHED;
;             PG8_LDB(B0, 1, 0); PG8_LDB(B1, 1, 1); PG8_SCHED; PG8_LDA(At, 1, 0); PG8_STAGE(PG8_SA(0, 1), a2 + hstepA, voffA);
;             PG8_WAIT_V(8); PG8_WAIT_L(0); PG8_BAR; PG8_MMA(0, 0, At, B0); PG8_MMA(0, 1, At, B1); PG8_BAR; PG8_SCHED;
	s_setprio 1
	s_waitcnt lgkmcnt(0)
	v_mfma_f32_16x16x32_bf16 v[92:95], v[148:151], v[188:191], v[92:95]
	v_mfma_f32_16x16x32_bf16 v[88:91], v[156:159], v[188:191], v[88:91]
	v_mfma_f32_16x16x32_bf16 v[84:87], v[148:151], v[196:199], v[84:87]
	v_mfma_f32_16x16x32_bf16 v[80:83], v[156:159], v[196:199], v[80:83]
	v_mfma_f32_16x16x32_bf16 v[76:79], v[148:151], v[204:207], v[76:79]
	v_mfma_f32_16x16x32_bf16 v[72:75], v[156:159], v[204:207], v[72:75]
	v_mfma_f32_16x16x32_bf16 v[68:71], v[148:151], v[214:217], v[68:71]
	v_mfma_f32_16x16x32_bf16 v[64:67], v[156:159], v[214:217], v[64:67]
	v_mfma_f32_16x16x32_bf16 v[92:95], v[152:155], v[192:195], v[92:95]
	v_mfma_f32_16x16x32_bf16 v[88:91], v[168:171], v[192:195], v[88:91]
	v_mfma_f32_16x16x32_bf16 v[84:87], v[152:155], v[200:203], v[84:87]
	v_mfma_f32_16x16x32_bf16 v[80:83], v[168:171], v[200:203], v[80:83]
	v_mfma_f32_16x16x32_bf16 v[76:79], v[152:155], v[210:213], v[76:79]
	v_mfma_f32_16x16x32_bf16 v[72:75], v[168:171], v[210:213], v[72:75]
	v_mfma_f32_16x16x32_bf16 v[68:71], v[152:155], v[218:221], v[68:71]
	v_mfma_f32_16x16x32_bf16 v[64:67], v[168:171], v[218:221], v[64:67]
	s_setprio 0
	s_setprio 1
	v_mfma_f32_16x16x32_bf16 v[28:31], v[172:175], v[188:191], v[28:31]
	v_mfma_f32_16x16x32_bf16 v[24:27], v[180:183], v[188:191], v[24:27]
	v_mfma_f32_16x16x32_bf16 v[20:23], v[172:175], v[196:199], v[20:23]
	v_mfma_f32_16x16x32_bf16 v[16:19], v[180:183], v[196:199], v[16:19]
	v_mfma_f32_16x16x32_bf16 v[12:15], v[172:175], v[204:207], v[12:15]
	v_mfma_f32_16x16x32_bf16 v[8:11], v[180:183], v[204:207], v[8:11]
	v_mfma_f32_16x16x32_bf16 v[4:7], v[172:175], v[214:217], v[4:7]
	v_mfma_f32_16x16x32_bf16 v[0:3], v[180:183], v[214:217], v[0:3]
	v_mfma_f32_16x16x32_bf16 v[28:31], v[176:179], v[192:195], v[28:31]
	v_mfma_f32_16x16x32_bf16 v[24:27], v[184:187], v[192:195], v[24:27]
	v_mfma_f32_16x16x32_bf16 v[20:23], v[176:179], v[200:203], v[20:23]
	v_mfma_f32_16x16x32_bf16 v[16:19], v[184:187], v[200:203], v[16:19]
	v_mfma_f32_16x16x32_bf16 v[12:15], v[176:179], v[210:213], v[12:15]
	v_mfma_f32_16x16x32_bf16 v[8:11], v[184:187], v[210:213], v[8:11]
	v_mfma_f32_16x16x32_bf16 v[4:7], v[176:179], v[218:221], v[4:7]
	v_mfma_f32_16x16x32_bf16 v[0:3], v[184:187], v[218:221], v[0:3]
	s_setprio 0
	s_barrier
	s_add_i32 s2, 0, 0x18000
	v_add_u32_e32 v136, s2, v161
	s_add_i32 s44, 0, 0x1c000
	ds_read_b128 v[148:151], v136
	ds_read_b128 v[152:155], v136 offset:1024
	ds_read_b128 v[156:159], v136 offset:2048
	ds_read_b128 v[168:171], v136 offset:3072
	v_add_u32_e32 v136, s44, v161
	ds_read_b128 v[172:175], v136
	ds_read_b128 v[176:179], v136 offset:1024
	ds_read_b128 v[180:183], v136 offset:2048
	ds_read_b128 v[184:187], v136 offset:3072
	s_add_u32 s40, s40, 0x80000
	s_addc_u32 s41, s41, 0
	s_mov_b32 m0, s55
	v_lshl_add_u64 v[230:231], s[40:41], 0, v[128:129]
	ds_read_b128 v[188:191], v165 offset:32768
	ds_read_b128 v[192:195], v165 offset:33792
	ds_read_b128 v[196:199], v165 offset:34816
	ds_read_b128 v[200:203], v165 offset:35840
	ds_read_b128 v[204:207], v165 offset:36864
	ds_read_b128 v[210:213], v165 offset:37888
	ds_read_b128 v[214:217], v165 offset:38912
	ds_read_b128 v[218:221], v165 offset:39936
	global_load_lds_dwordx4 v[230:231], off
	v_lshl_add_u64 v[230:231], s[40:41], 0, v[132:133]
	s_mov_b32 m0, s56
	s_nop 0
	global_load_lds_dwordx4 v[230:231], off
	s_waitcnt vmcnt(16)
	s_waitcnt lgkmcnt(0)
	s_barrier
	s_setprio 1
	s_waitcnt lgkmcnt(0)
	v_mfma_f32_16x16x32_bf16 v[124:127], v[148:151], v[188:191], v[124:127]
	v_mfma_f32_16x16x32_bf16 v[120:123], v[156:159], v[188:191], v[120:123]
	v_mfma_f32_16x16x32_bf16 v[116:119], v[148:151], v[196:199], v[116:119]
	v_mfma_f32_16x16x32_bf16 v[112:115], v[156:159], v[196:199], v[112:115]
	v_mfma_f32_16x16x32_bf16 v[108:111], v[148:151], v[204:207], v[108:111]
	v_mfma_f32_16x16x32_bf16 v[104:107], v[156:159], v[204:207], v[104:107]
	v_mfma_f32_16x16x32_bf16 v[100:103], v[148:151], v[214:217], v[100:103]
	v_mfma_f32_16x16x32_bf16 v[96:99], v[156:159], v[214:217], v[96:99]
	v_mfma_f32_16x16x32_bf16 v[124:127], v[152:155], v[192:195], v[124:127]
	v_mfma_f32_16x16x32_bf16 v[120:123], v[168:171], v[192:195], v[120:123]
	v_mfma_f32_16x16x32_bf16 v[116:119], v[152:155], v[200:203], v[116:119]
	v_mfma_f32_16x16x32_bf16 v[112:115], v[168:171], v[200:203], v[112:115]
	v_mfma_f32_16x16x32_bf16 v[108:111], v[152:155], v[210:213], v[108:111]
	v_mfma_f32_16x16x32_bf16 v[104:107], v[168:171], v[210:213], v[104:107]
	v_mfma_f32_16x16x32_bf16 v[100:103], v[152:155], v[218:221], v[100:103]
	v_mfma_f32_16x16x32_bf16 v[96:99], v[168:171], v[218:221], v[96:99]
	s_setprio 0
	s_setprio 1
	v_mfma_f32_16x16x32_bf16 v[60:63], v[172:175], v[188:191], v[60:63]
	v_mfma_f32_16x16x32_bf16 v[56:59], v[180:183], v[188:191], v[56:59]
	v_mfma_f32_16x16x32_bf16 v[52:55], v[172:175], v[196:199], v[52:55]
	v_mfma_f32_16x16x32_bf16 v[48:51], v[180:183], v[196:199], v[48:51]
	v_mfma_f32_16x16x32_bf16 v[44:47], v[172:175], v[204:207], v[44:47]
	v_mfma_f32_16x16x32_bf16 v[40:43], v[180:183], v[204:207], v[40:43]
	v_mfma_f32_16x16x32_bf16 v[36:39], v[172:175], v[214:217], v[36:39]
	v_mfma_f32_16x16x32_bf16 v[32:35], v[180:183], v[214:217], v[32:35]
	v_mfma_f32_16x16x32_bf16 v[60:63], v[176:179], v[192:195], v[60:63]
	v_mfma_f32_16x16x32_bf16 v[56:59], v[184:187], v[192:195], v[56:59]
	v_mfma_f32_16x16x32_bf16 v[52:55], v[176:179], v[200:203], v[52:55]
	v_mfma_f32_16x16x32_bf16 v[48:51], v[184:187], v[200:203], v[48:51]
	v_mfma_f32_16x16x32_bf16 v[44:47], v[176:179], v[210:213], v[44:47]
	v_mfma_f32_16x16x32_bf16 v[40:43], v[184:187], v[210:213], v[40:43]
	v_mfma_f32_16x16x32_bf16 v[36:39], v[176:179], v[218:221], v[36:39]
	v_mfma_f32_16x16x32_bf16 v[32:35], v[184:187], v[218:221], v[32:35]
	s_setprio 0
	s_barrier
; #define LAS __attribute__((address_space(3)))
; __device__ __forceinline__ unsigned pk2_rne(float lo, float hi) { const f32x2_t f = {lo, hi}; return __builtin_bit_cast(unsigned, __builtin_convertvector(f, bf16x2_t)); }
; #define PG8_STAGE(bufoff, gbase, voff) do { _Pragma("unroll") for (int _i = 0; _i < 2; ++_i) \
;         __builtin_amdgcn_global_load_lds((const unsigned*)((const char*)(gbase) + (voff)[_i]), (LAS unsigned*)(lds + (bufoff) + ldsw + _i * 8192), 16, 0, 0); } while (0)
; #define PG8_LDA(dst, b, h) do { _Pragma("unroll") for (int m = 0; m < 4; ++m) _Pragma("unroll") for (int k = 0; k < 2; ++k) dst[m][k] = *(const LAS bf16x8*)(lds + PG8_SA(b, h) + aoff + m * 2048 + k * 1024); } while (0)
; #define PG8_MMA(ai, bj, At, Bt) do { __builtin_amdgcn_s_setprio(1); _Pragma("unroll") for (int m = 0; m < 4; ++m) _Pragma("unroll") for (int n = 0; n < 2; ++n) _Pragma("unroll") for (int k = 0; k < 2; ++k) \
;         acc[ai][bj][m][n] = __builtin_amdgcn_mfma_f32_16x16x32_bf16(Bt[n][k], At[m][k], acc[ai][bj][m][n], 0, 0, 0); __builtin_amdgcn_s_setprio(0); } while (0)
; #define PG8_WAIT_V(n) asm volatile("s_waitcnt vmcnt(" #n ")" ::: "memory")
; #define PG8_WAIT_L(n) asm volatile("s_waitcnt lgkmcnt(" #n ")" ::: "memory")
; #define PG8_BAR __builtin_amdgcn_s_barrier()
; #define PG8_SCHED __builtin_amdgcn_sched_barrier(0)
; template <class Epi, class Sched>
; __device__ __forceinline__ void gemm_phase(LAS unsigned char* lds, const Gemm g, const Sched& S, const Epi& E) {
;     ...
;             PG8_LDA(At, 1, 1); PG8_STAGE(PG8_SB(1, 0), b3, voffB); PG8_STAGE(PG8_SB(1, 1), b3 + hstepB, voffB); PG8_STAGE(PG8_SA(1, 0), a3, voffA);
;             PG8_WAIT_V(8); PG8_WAIT_L(0); PG8_BAR; PG8_MMA(1, 0, At, B0); PG8_MMA(1, 1, At, B1); PG8_BAR; PG8_SCHED;
; __device__ __forceinline__ void transpose_item(const float* __restrict__ W, int K, int N, bf16_t* __restrict__ WT, LAS float* scr, int item, int lane, bool upmap = false) {
;     ...
;         const int n = (lane >> 3) + 8 * j; const LAS float* s = scr + (8 * cch) * 65 + n;
;         u32x4 o; o.x = pk2_rne(s[0], s[65]); o.y = pk2_rne(s[2 * 65], s[3 * 65]); o.z = pk2_rne(s[4 * 65], s[5 * 65]); o.w = pk2_rne(s[6 * 65], s[7 * 65]);
	s_add_i32 s2, s2, s52
	v_lshl_add_u64 v[222:223], v[222:223], 0, s[18:19]
	s_mov_b32 m0, s2
	ds_read_b128 v[188:191], v165 offset:49152
	ds_read_b128 v[192:195], v165 offset:50176
	ds_read_b128 v[196:199], v165 offset:51200
	ds_read_b128 v[200:203], v165 offset:52224
	ds_read_b128 v[204:207], v165 offset:53248
	ds_read_b128 v[210:213], v165 offset:54272
	ds_read_b128 v[214:217], v165 offset:55296
	ds_read_b128 v[218:221], v165 offset:56320
	global_load_lds_dwordx4 v[222:223], off
	s_add_i32 m0, s2, 0x2000
	s_add_u32 s12, s12, 0x80080
	v_lshl_add_u64 v[222:223], v[224:225], 0, s[18:19]
	s_addc_u32 s13, s13, 0
	s_add_i32 s2, s44, s52
	global_load_lds_dwordx4 v[222:223], off
	v_lshl_add_u64 v[222:223], s[12:13], 0, v[130:131]
	s_mov_b32 m0, s2
	s_nop 0
	global_load_lds_dwordx4 v[222:223], off
	v_lshl_add_u64 v[222:223], s[12:13], 0, v[134:135]
	s_add_i32 m0, s2, 0x2000
	s_nop 0
	global_load_lds_dwordx4 v[222:223], off
	v_lshl_add_u64 v[222:223], v[226:227], 0, s[18:19]
	s_mov_b32 m0, s58
	s_nop 0
	global_load_lds_dwordx4 v[222:223], off
	v_lshl_add_u64 v[222:223], v[228:229], 0, s[18:19]
	s_mov_b32 m0, s59
	s_nop 0
	global_load_lds_dwordx4 v[222:223], off
	s_waitcnt vmcnt(8)
	s_waitcnt lgkmcnt(0)
	s_barrier
	s_setprio 1
	s_waitcnt lgkmcnt(0)
	v_mfma_f32_16x16x32_bf16 v[92:95], v[148:151], v[188:191], v[92:95]
	v_mfma_f32_16x16x32_bf16 v[88:91], v[156:159], v[188:191], v[88:91]
	v_mfma_f32_16x16x32_bf16 v[84:87], v[148:151], v[196:199], v[84:87]
	v_mfma_f32_16x16x32_bf16 v[80:83], v[156:159], v[196:199], v[80:83]
	v_mfma_f32_16x16x32_bf16 v[76:79], v[148:151], v[204:207], v[76:79]
	v_mfma_f32_16x16x32_bf16 v[72:75], v[156:159], v[204:207], v[72:75]
	v_mfma_f32_16x16x32_bf16 v[68:71], v[148:151], v[214:217], v[68:71]
	v_mfma_f32_16x16x32_bf16 v[64:67], v[156:159], v[214:217], v[64:67]
	v_mfma_f32_16x16x32_bf16 v[92:95], v[152:155], v[192:195], v[92:95]
	v_mfma_f32_16x16x32_bf16 v[88:91], v[168:171], v[192:195], v[88:91]
	v_mfma_f32_16x16x32_bf16 v[84:87], v[152:155], v[200:203], v[84:87]
	v_mfma_f32_16x16x32_bf16 v[80:83], v[168:171], v[200:203], v[80:83]
	v_mfma_f32_16x16x32_bf16 v[76:79], v[152:155], v[210:213], v[76:79]
	v_mfma_f32_16x16x32_bf16 v[72:75], v[168:171], v[210:213], v[72:75]
	v_mfma_f32_16x16x32_bf16 v[68:71], v[152:155], v[218:221], v[68:71]
	v_mfma_f32_16x16x32_bf16 v[64:67], v[168:171], v[218:221], v[64:67]
	s_setprio 0
	s_setprio 1
	v_mfma_f32_16x16x32_bf16 v[28:31], v[172:175], v[188:191], v[28:31]
	v_mfma_f32_16x16x32_bf16 v[24:27], v[180:183], v[188:191], v[24:27]
	v_mfma_f32_16x16x32_bf16 v[20:23], v[172:175], v[196:199], v[20:23]
	v_mfma_f32_16x16x32_bf16 v[16:19], v[180:183], v[196:199], v[16:19]
	v_mfma_f32_16x16x32_bf16 v[12:15], v[172:175], v[204:207], v[12:15]
	v_mfma_f32_16x16x32_bf16 v[8:11], v[180:183], v[204:207], v[8:11]
	v_mfma_f32_16x16x32_bf16 v[4:7], v[172:175], v[214:217], v[4:7]
	v_mfma_f32_16x16x32_bf16 v[0:3], v[180:183], v[214:217], v[0:3]
	v_mfma_f32_16x16x32_bf16 v[28:31], v[176:179], v[192:195], v[28:31]
	v_mfma_f32_16x16x32_bf16 v[24:27], v[184:187], v[192:195], v[24:27]
	v_mfma_f32_16x16x32_bf16 v[20:23], v[176:179], v[200:203], v[20:23]
	v_mfma_f32_16x16x32_bf16 v[16:19], v[184:187], v[200:203], v[16:19]
	v_mfma_f32_16x16x32_bf16 v[12:15], v[176:179], v[210:213], v[12:15]
	v_mfma_f32_16x16x32_bf16 v[8:11], v[184:187], v[210:213], v[8:11]
	v_mfma_f32_16x16x32_bf16 v[4:7], v[176:179], v[218:221], v[4:7]
	v_mfma_f32_16x16x32_bf16 v[0:3], v[184:187], v[218:221], v[0:3]
	s_setprio 0
	s_barrier
	v_cvt_pk_bf16_f32 v148, v232, v234
	v_cvt_pk_bf16_f32 v149, v236, v238
	v_cvt_pk_bf16_f32 v152, v233, v235
	v_cvt_pk_bf16_f32 v153, v237, v239
	v_accvgpr_read_b32 v168, a0
	v_accvgpr_read_b32 v169, a2
	v_accvgpr_read_b32 v170, a4
	v_accvgpr_read_b32 v171, a6
	v_accvgpr_read_b32 v172, a1
	v_accvgpr_read_b32 v173, a3
	v_accvgpr_read_b32 v174, a5
	v_accvgpr_read_b32 v175, a7
	v_cvt_pk_bf16_f32 v150, v168, v169
	v_cvt_pk_bf16_f32 v151, v170, v171
	v_cvt_pk_bf16_f32 v154, v172, v173
	v_cvt_pk_bf16_f32 v155, v174, v175
	s_cmp_eq_u32 s43, 14
	s_cbranch_scc1 .Lwc_keep
	s_lshl_b32 s32, s97, 11
	s_add_i32 s32, s32, 0x20000
	v_lshl_add_u32 v168, v208, 4, s32
	ds_write_b128 v168, v[148:151]
	ds_write_b128 v168, v[152:155] offset:1024
	s_branch .Lwc_packed
.Lwc_keep:
	v_mov_b32_e32 v232, v148
	v_mov_b32_e32 v233, v149
	v_mov_b32_e32 v234, v150
	v_mov_b32_e32 v235, v151
	v_mov_b32_e32 v236, v152
	v_mov_b32_e32 v237, v153
	v_mov_b32_e32 v238, v154
	v_mov_b32_e32 v239, v155
.Lwc_packed:
	s_add_i32 s43, s43, 2
	s_add_u32 s8, s8, 0x100
	s_addc_u32 s9, s9, 0
	s_add_u32 s35, s35, 0x100
	s_addc_u32 s42, s42, 0
; #define PG8_STAGE(bufoff, gbase, voff) do { _Pragma("unroll") for (int _i = 0; _i < 2; ++_i) \
;         __builtin_amdgcn_global_load_lds((const unsigned*)((const char*)(gbase) + (voff)[_i]), (LAS unsigned*)(lds + (bufoff) + ldsw + _i * 8192), 16, 0, 0); } while (0)
; #define PG8_LDA(dst, b, h) do { _Pragma("unroll") for (int m = 0; m < 4; ++m) _Pragma("unroll") for (int k = 0; k < 2; ++k) dst[m][k] = *(const LAS bf16x8*)(lds + PG8_SA(b, h) + aoff + m * 2048 + k * 1024); } while (0)
; #define PG8_LDB(dst, b, h) do { _Pragma("unroll") for (int n = 0; n < 2; ++n) _Pragma("unroll") for (int k = 0; k < 2; ++k) dst[n][k] = *(const LAS bf16x8*)(lds + PG8_SB(b, h) + boff + n * 2048 + k * 1024); } while (0)
; #define PG8_MMA(ai, bj, At, Bt) do { __builtin_amdgcn_s_setprio(1); _Pragma("unroll") for (int m = 0; m < 4; ++m) _Pragma("unroll") for (int n = 0; n < 2; ++n) _Pragma("unroll") for (int k = 0; k < 2; ++k) \
;         acc[ai][bj][m][n] = __builtin_amdgcn_mfma_f32_16x16x32_bf16(Bt[n][k], At[m][k], acc[ai][bj][m][n], 0, 0, 0); __builtin_amdgcn_s_setprio(0); } while (0)
; #define PG8_WAIT_V(n) asm volatile("s_waitcnt vmcnt(" #n ")" ::: "memory")
; #define PG8_WAIT_L(n) asm volatile("s_waitcnt lgkmcnt(" #n ")" ::: "memory")
; #define PG8_BAR __builtin_amdgcn_s_barrier()
; #define PG8_SCHED __builtin_amdgcn_sched_barrier(0)
; template <class Epi, class Sched>
; __device__ __forceinline__ void gemm_phase(LAS unsigned char* lds, const Gemm g, const Sched& S, const Epi& E) {
;     ...
;         for (int t = 0; t < nt; t += 2) {
;             const bool last = (t == nt - 2);
;             const char* a1 = cA + (size_t)(t + 1) * kstep;
;             const char* a2 = last ? nA : cA + (size_t)(t + 2) * kstep; const char* b2 = last ? nB : cB + (size_t)(t + 2) * kstep;
;             const char* a3 = a2 + kstep; const char* b3 = b2 + kstep;
;             PG8_LDB(B0, 0, 0); PG8_LDB(B1, 0, 1); PG8_SCHED; PG8_LDA(At, 0, 0); PG8_STAGE(PG8_SA(1, 1), a1 + hstepA, voffA);
;             PG8_WAIT_V(8); PG8_WAIT_L(0); PG8_BAR; PG8_MMA(0, 0, At, B0); PG8_MMA(0, 1, At, B1); PG8_BAR; PG8_SCHED;
;             PG8_LDA(At, 0, 1); PG8_STAGE(PG8_SB(0, 0), b2, voffB); PG8_STAGE(PG8_SB(0, 1), b2 + hstepB, voffB); PG8_STAGE(PG8_SA(0, 0), a2, voffA);
;             PG8_WAIT_V(8); PG8_WAIT_L(0); PG8_BAR; PG8_MMA(1, 0, At, B0); PG8_MMA(1, 1, At, B1); PG8_BAR; PG8_SCHED;
.Lwc_N:
	ds_read_b128 v[148:151], v163
	ds_read_b128 v[152:155], v163 offset:1024
	ds_read_b128 v[156:159], v163 offset:2048
	ds_read_b128 v[168:171], v163 offset:3072
	ds_read_b128 v[172:175], v164
	ds_read_b128 v[176:179], v164 offset:1024
	ds_read_b128 v[180:183], v164 offset:2048
	ds_read_b128 v[184:187], v164 offset:3072
	s_add_u32 s2, s8, 0xfff80080
	s_addc_u32 s12, s9, -1
	s_cmp_eq_u32 s43, 28
	s_cselect_b32 s41, s7, s12
	s_cselect_b32 s40, s11, s2
	s_cselect_b32 s13, s31, s42
	s_cselect_b32 s12, s33, s35
	v_lshl_add_u64 v[222:223], s[8:9], 0, v[140:141]
	s_add_i32 m0, s53, 0xc000
	ds_read_b128 v[188:191], v165
	ds_read_b128 v[192:195], v165 offset:1024
	ds_read_b128 v[196:199], v165 offset:2048
	ds_read_b128 v[200:203], v165 offset:3072
	ds_read_b128 v[204:207], v165 offset:4096
	ds_read_b128 v[210:213], v165 offset:5120
	ds_read_b128 v[214:217], v165 offset:6144
	ds_read_b128 v[218:221], v165 offset:7168
	global_load_lds_dwordx4 v[222:223], off
	v_lshl_add_u64 v[222:223], s[8:9], 0, v[142:143]
	s_add_i32 m0, s53, 0xe000
	s_nop 0
	global_load_lds_dwordx4 v[222:223], off
	s_waitcnt vmcnt(8)
	s_waitcnt lgkmcnt(0)
	s_barrier
	s_setprio 1
	s_waitcnt lgkmcnt(0)
	v_mfma_f32_16x16x32_bf16 v[124:127], v[148:151], v[188:191], v[124:127]
	v_mfma_f32_16x16x32_bf16 v[120:123], v[156:159], v[188:191], v[120:123]
	v_mfma_f32_16x16x32_bf16 v[116:119], v[148:151], v[196:199], v[116:119]
	v_mfma_f32_16x16x32_bf16 v[112:115], v[156:159], v[196:199], v[112:115]
	v_mfma_f32_16x16x32_bf16 v[108:111], v[148:151], v[204:207], v[108:111]
	v_mfma_f32_16x16x32_bf16 v[104:107], v[156:159], v[204:207], v[104:107]
	v_mfma_f32_16x16x32_bf16 v[100:103], v[148:151], v[214:217], v[100:103]
	v_mfma_f32_16x16x32_bf16 v[96:99], v[156:159], v[214:217], v[96:99]
	v_mfma_f32_16x16x32_bf16 v[124:127], v[152:155], v[192:195], v[124:127]
	v_mfma_f32_16x16x32_bf16 v[120:123], v[168:171], v[192:195], v[120:123]
	v_mfma_f32_16x16x32_bf16 v[116:119], v[152:155], v[200:203], v[116:119]
	v_mfma_f32_16x16x32_bf16 v[112:115], v[168:171], v[200:203], v[112:115]
	v_mfma_f32_16x16x32_bf16 v[108:111], v[152:155], v[210:213], v[108:111]
	v_mfma_f32_16x16x32_bf16 v[104:107], v[168:171], v[210:213], v[104:107]
	v_mfma_f32_16x16x32_bf16 v[100:103], v[152:155], v[218:221], v[100:103]
	v_mfma_f32_16x16x32_bf16 v[96:99], v[168:171], v[218:221], v[96:99]
	s_setprio 0
	s_setprio 1
	v_mfma_f32_16x16x32_bf16 v[60:63], v[172:175], v[188:191], v[60:63]
	v_mfma_f32_16x16x32_bf16 v[56:59], v[180:183], v[188:191], v[56:59]
	v_mfma_f32_16x16x32_bf16 v[52:55], v[172:175], v[196:199], v[52:55]
	v_mfma_f32_16x16x32_bf16 v[48:51], v[180:183], v[196:199], v[48:51]
	v_mfma_f32_16x16x32_bf16 v[44:47], v[172:175], v[204:207], v[44:47]
	v_mfma_f32_16x16x32_bf16 v[40:43], v[180:183], v[204:207], v[40:43]
	v_mfma_f32_16x16x32_bf16 v[36:39], v[172:175], v[214:217], v[36:39]
	v_mfma_f32_16x16x32_bf16 v[32:35], v[180:183], v[214:217], v[32:35]
	v_mfma_f32_16x16x32_bf16 v[60:63], v[176:179], v[192:195], v[60:63]
	v_mfma_f32_16x16x32_bf16 v[56:59], v[184:187], v[192:195], v[56:59]
	v_mfma_f32_16x16x32_bf16 v[52:55], v[176:179], v[200:203], v[52:55]
	v_mfma_f32_16x16x32_bf16 v[48:51], v[184:187], v[200:203], v[48:51]
	v_mfma_f32_16x16x32_bf16 v[44:47], v[176:179], v[210:213], v[44:47]
	v_mfma_f32_16x16x32_bf16 v[40:43], v[184:187], v[210:213], v[40:43]
	v_mfma_f32_16x16x32_bf16 v[36:39], v[176:179], v[218:221], v[36:39]
	v_mfma_f32_16x16x32_bf16 v[32:35], v[184:187], v[218:221], v[32:35]
	s_setprio 0
	s_barrier
	s_add_i32 s2, s64, s52
	v_lshl_add_u64 v[222:223], s[12:13], 0, v[130:131]
	s_mov_b32 m0, s2
	ds_read_b128 v[188:191], v165 offset:16384
	ds_read_b128 v[192:195], v165 offset:17408
	ds_read_b128 v[196:199], v165 offset:18432
	ds_read_b128 v[200:203], v165 offset:19456
	ds_read_b128 v[204:207], v165 offset:20480
	ds_read_b128 v[210:213], v165 offset:21504
	ds_read_b128 v[214:217], v165 offset:22528
	ds_read_b128 v[218:221], v165 offset:23552
	global_load_lds_dwordx4 v[222:223], off
	s_add_i32 m0, s2, 0x2000
	s_add_u32 s44, s12, 0x80000
	v_lshl_add_u64 v[224:225], s[12:13], 0, v[134:135]
	s_addc_u32 s45, s13, 0
	s_add_i32 s2, s65, s52
	global_load_lds_dwordx4 v[224:225], off
	v_lshl_add_u64 v[226:227], s[44:45], 0, v[130:131]
	s_mov_b32 m0, s2
	v_lshl_add_u64 v[228:229], s[40:41], 0, v[132:133]
	global_load_lds_dwordx4 v[226:227], off
	v_lshl_add_u64 v[226:227], s[44:45], 0, v[134:135]
	s_add_i32 m0, s2, 0x2000
	s_nop 0
	global_load_lds_dwordx4 v[226:227], off
	v_lshl_add_u64 v[226:227], s[40:41], 0, v[128:129]
	s_mov_b32 m0, s53
	s_nop 0
	global_load_lds_dwordx4 v[226:227], off
	s_mov_b32 m0, s54
	s_nop 0
	global_load_lds_dwordx4 v[228:229], off
	s_waitcnt vmcnt(8)
	s_waitcnt lgkmcnt(0)
	s_barrier
; #define PG8_STAGE(bufoff, gbase, voff) do { _Pragma("unroll") for (int _i = 0; _i < 2; ++_i) \
;         __builtin_amdgcn_global_load_lds((const unsigned*)((const char*)(gbase) + (voff)[_i]), (LAS unsigned*)(lds + (bufoff) + ldsw + _i * 8192), 16, 0, 0); } while (0)
; #define PG8_LDA(dst, b, h) do { _Pragma("unroll") for (int m = 0; m < 4; ++m) _Pragma("unroll") for (int k = 0; k < 2; ++k) dst[m][k] = *(const LAS bf16x8*)(lds + PG8_SA(b, h) + aoff + m * 2048 + k * 1024); } while (0)
; #define PG8_LDB(dst, b, h) do { _Pragma("unroll") for (int n = 0; n < 2; ++n) _Pragma("unroll") for (int k = 0; k < 2; ++k) dst[n][k] = *(const LAS bf16x8*)(lds + PG8_SB(b, h) + boff + n * 2048 + k * 1024); } while (0)
; #define PG8_MMA(ai, bj, At, Bt) do { __builtin_amdgcn_s_setprio(1); _Pragma("unroll") for (int m = 0; m < 4; ++m) _Pragma("unroll") for (int n = 0; n < 2; ++n) _Pragma("unroll") for (int k = 0; k < 2; ++k) \
;         acc[ai][bj][m][n] = __builtin_amdgcn_mfma_f32_16x16x32_bf16(Bt[n][k], At[m][k], acc[ai][bj][m][n], 0, 0, 0); __builtin_amdgcn_s_setprio(0); } while (0)
; #define PG8_WAIT_V(n) asm volatile("s_waitcnt vmcnt(" #n ")" ::: "memory")
; #define PG8_WAIT_L(n) asm volatile("s_waitcnt lgkmcnt(" #n ")" ::: "memory")
; #define PG8_BAR __builtin_amdgcn_s_barrier()
; #define PG8_SCHED __builtin_amdgcn_sched_barrier(0)
; template <class Epi, class Sched>
; __device__ __forceinline__ void gemm_phase(LAS unsigned char* lds, const Gemm g, const Sched& S, const Epi& E) {
;     ...
;             PG8_WAIT_V(8); PG8_WAIT_L(0); PG8_BAR; PG8_MMA(1, 0, At, B0); PG8_MMA(1, 1, At, B1); PG8_BAR; PG8_SCHED;
;             PG8_LDB(B0, 1, 0); PG8_LDB(B1, 1, 1); PG8_SCHED; PG8_LDA(At, 1, 0); PG8_STAGE(PG8_SA(0, 1), a2 + hstepA, voffA);
;             PG8_WAIT_V(8); PG8_WAIT_L(0); PG8_BAR; PG8_MMA(0, 0, At, B0); PG8_MMA(0, 1, At, B1); PG8_BAR; PG8_SCHED;
	s_setprio 1
	s_waitcnt lgkmcnt(0)
	v_mfma_f32_16x16x32_bf16 v[92:95], v[148:151], v[188:191], v[92:95]
	v_mfma_f32_16x16x32_bf16 v[88:91], v[156:159], v[188:191], v[88:91]
	v_mfma_f32_16x16x32_bf16 v[84:87], v[148:151], v[196:199], v[84:87]
	v_mfma_f32_16x16x32_bf16 v[80:83], v[156:159], v[196:199], v[80:83]
	v_mfma_f32_16x16x32_bf16 v[76:79], v[148:151], v[204:207], v[76:79]
	v_mfma_f32_16x16x32_bf16 v[72:75], v[156:159], v[204:207], v[72:75]
	v_mfma_f32_16x16x32_bf16 v[68:71], v[148:151], v[214:217], v[68:71]
	v_mfma_f32_16x16x32_bf16 v[64:67], v[156:159], v[214:217], v[64:67]
	v_mfma_f32_16x16x32_bf16 v[92:95], v[152:155], v[192:195], v[92:95]
	v_mfma_f32_16x16x32_bf16 v[88:91], v[168:171], v[192:195], v[88:91]
	v_mfma_f32_16x16x32_bf16 v[84:87], v[152:155], v[200:203], v[84:87]
	v_mfma_f32_16x16x32_bf16 v[80:83], v[168:171], v[200:203], v[80:83]
	v_mfma_f32_16x16x32_bf16 v[76:79], v[152:155], v[210:213], v[76:79]
	v_mfma_f32_16x16x32_bf16 v[72:75], v[168:171], v[210:213], v[72:75]
	v_mfma_f32_16x16x32_bf16 v[68:71], v[152:155], v[218:221], v[68:71]
	v_mfma_f32_16x16x32_bf16 v[64:67], v[168:171], v[218:221], v[64:67]
	s_setprio 0
	s_setprio 1
	v_mfma_f32_16x16x32_bf16 v[28:31], v[172:175], v[188:191], v[28:31]
	v_mfma_f32_16x16x32_bf16 v[24:27], v[180:183], v[188:191], v[24:27]
	v_mfma_f32_16x16x32_bf16 v[20:23], v[172:175], v[196:199], v[20:23]
	v_mfma_f32_16x16x32_bf16 v[16:19], v[180:183], v[196:199], v[16:19]
	v_mfma_f32_16x16x32_bf16 v[12:15], v[172:175], v[204:207], v[12:15]
	v_mfma_f32_16x16x32_bf16 v[8:11], v[180:183], v[204:207], v[8:11]
	v_mfma_f32_16x16x32_bf16 v[4:7], v[172:175], v[214:217], v[4:7]
	v_mfma_f32_16x16x32_bf16 v[0:3], v[180:183], v[214:217], v[0:3]
	v_mfma_f32_16x16x32_bf16 v[28:31], v[176:179], v[192:195], v[28:31]
	v_mfma_f32_16x16x32_bf16 v[24:27], v[184:187], v[192:195], v[24:27]
	v_mfma_f32_16x16x32_bf16 v[20:23], v[176:179], v[200:203], v[20:23]
	v_mfma_f32_16x16x32_bf16 v[16:19], v[184:187], v[200:203], v[16:19]
	v_mfma_f32_16x16x32_bf16 v[12:15], v[176:179], v[210:213], v[12:15]
	v_mfma_f32_16x16x32_bf16 v[8:11], v[184:187], v[210:213], v[8:11]
	v_mfma_f32_16x16x32_bf16 v[4:7], v[176:179], v[218:221], v[4:7]
	v_mfma_f32_16x16x32_bf16 v[0:3], v[184:187], v[218:221], v[0:3]
	s_setprio 0
	s_barrier
	s_add_i32 s2, 0, 0x18000
	v_add_u32_e32 v136, s2, v161
	s_add_i32 s44, 0, 0x1c000
	ds_read_b128 v[148:151], v136
	ds_read_b128 v[152:155], v136 offset:1024
	ds_read_b128 v[156:159], v136 offset:2048
	ds_read_b128 v[168:171], v136 offset:3072
	v_add_u32_e32 v136, s44, v161
	ds_read_b128 v[172:175], v136
	ds_read_b128 v[176:179], v136 offset:1024
	ds_read_b128 v[180:183], v136 offset:2048
	ds_read_b128 v[184:187], v136 offset:3072
	s_add_u32 s40, s40, 0x80000
	s_addc_u32 s41, s41, 0
	s_mov_b32 m0, s55
	v_lshl_add_u64 v[230:231], s[40:41], 0, v[128:129]
	ds_read_b128 v[188:191], v165 offset:32768
	ds_read_b128 v[192:195], v165 offset:33792
	ds_read_b128 v[196:199], v165 offset:34816
	ds_read_b128 v[200:203], v165 offset:35840
	ds_read_b128 v[204:207], v165 offset:36864
	ds_read_b128 v[210:213], v165 offset:37888
	ds_read_b128 v[214:217], v165 offset:38912
	ds_read_b128 v[218:221], v165 offset:39936
	global_load_lds_dwordx4 v[230:231], off
	v_lshl_add_u64 v[230:231], s[40:41], 0, v[132:133]
	s_mov_b32 m0, s56
	s_nop 0
	global_load_lds_dwordx4 v[230:231], off
	s_waitcnt vmcnt(8)
	s_waitcnt lgkmcnt(0)
	s_barrier
	s_setprio 1
	s_waitcnt lgkmcnt(0)
	v_mfma_f32_16x16x32_bf16 v[124:127], v[148:151], v[188:191], v[124:127]
	v_mfma_f32_16x16x32_bf16 v[120:123], v[156:159], v[188:191], v[120:123]
	v_mfma_f32_16x16x32_bf16 v[116:119], v[148:151], v[196:199], v[116:119]
	v_mfma_f32_16x16x32_bf16 v[112:115], v[156:159], v[196:199], v[112:115]
	v_mfma_f32_16x16x32_bf16 v[108:111], v[148:151], v[204:207], v[108:111]
	v_mfma_f32_16x16x32_bf16 v[104:107], v[156:159], v[204:207], v[104:107]
	v_mfma_f32_16x16x32_bf16 v[100:103], v[148:151], v[214:217], v[100:103]
	v_mfma_f32_16x16x32_bf16 v[96:99], v[156:159], v[214:217], v[96:99]
	v_mfma_f32_16x16x32_bf16 v[124:127], v[152:155], v[192:195], v[124:127]
	v_mfma_f32_16x16x32_bf16 v[120:123], v[168:171], v[192:195], v[120:123]
	v_mfma_f32_16x16x32_bf16 v[116:119], v[152:155], v[200:203], v[116:119]
	v_mfma_f32_16x16x32_bf16 v[112:115], v[168:171], v[200:203], v[112:115]
	v_mfma_f32_16x16x32_bf16 v[108:111], v[152:155], v[210:213], v[108:111]
	v_mfma_f32_16x16x32_bf16 v[104:107], v[168:171], v[210:213], v[104:107]
	v_mfma_f32_16x16x32_bf16 v[100:103], v[152:155], v[218:221], v[100:103]
	v_mfma_f32_16x16x32_bf16 v[96:99], v[168:171], v[218:221], v[96:99]
	s_setprio 0
	s_setprio 1
	v_mfma_f32_16x16x32_bf16 v[60:63], v[172:175], v[188:191], v[60:63]
	v_mfma_f32_16x16x32_bf16 v[56:59], v[180:183], v[188:191], v[56:59]
	v_mfma_f32_16x16x32_bf16 v[52:55], v[172:175], v[196:199], v[52:55]
	v_mfma_f32_16x16x32_bf16 v[48:51], v[180:183], v[196:199], v[48:51]
	v_mfma_f32_16x16x32_bf16 v[44:47], v[172:175], v[204:207], v[44:47]
	v_mfma_f32_16x16x32_bf16 v[40:43], v[180:183], v[204:207], v[40:43]
	v_mfma_f32_16x16x32_bf16 v[36:39], v[172:175], v[214:217], v[36:39]
	v_mfma_f32_16x16x32_bf16 v[32:35], v[180:183], v[214:217], v[32:35]
	v_mfma_f32_16x16x32_bf16 v[60:63], v[176:179], v[192:195], v[60:63]
	v_mfma_f32_16x16x32_bf16 v[56:59], v[184:187], v[192:195], v[56:59]
	v_mfma_f32_16x16x32_bf16 v[52:55], v[176:179], v[200:203], v[52:55]
	v_mfma_f32_16x16x32_bf16 v[48:51], v[184:187], v[200:203], v[48:51]
	v_mfma_f32_16x16x32_bf16 v[44:47], v[176:179], v[210:213], v[44:47]
	v_mfma_f32_16x16x32_bf16 v[40:43], v[184:187], v[210:213], v[40:43]
	v_mfma_f32_16x16x32_bf16 v[36:39], v[176:179], v[218:221], v[36:39]
	v_mfma_f32_16x16x32_bf16 v[32:35], v[184:187], v[218:221], v[32:35]
	s_setprio 0
	s_barrier
; #define PG8_STAGE(bufoff, gbase, voff) do { _Pragma("unroll") for (int _i = 0; _i < 2; ++_i) \
;         __builtin_amdgcn_global_load_lds((const unsigned*)((const char*)(gbase) + (voff)[_i]), (LAS unsigned*)(lds + (bufoff) + ldsw + _i * 8192), 16, 0, 0); } while (0)
; #define PG8_LDA(dst, b, h) do { _Pragma("unroll") for (int m = 0; m < 4; ++m) _Pragma("unroll") for (int k = 0; k < 2; ++k) dst[m][k] = *(const LAS bf16x8*)(lds + PG8_SA(b, h) + aoff + m * 2048 + k * 1024); } while (0)
; #define PG8_MMA(ai, bj, At, Bt) do { __builtin_amdgcn_s_setprio(1); _Pragma("unroll") for (int m = 0; m < 4; ++m) _Pragma("unroll") for (int n = 0; n < 2; ++n) _Pragma("unroll") for (int k = 0; k < 2; ++k) \
;         acc[ai][bj][m][n] = __builtin_amdgcn_mfma_f32_16x16x32_bf16(Bt[n][k], At[m][k], acc[ai][bj][m][n], 0, 0, 0); __builtin_amdgcn_s_setprio(0); } while (0)
; #define PG8_WAIT_V(n) asm volatile("s_waitcnt vmcnt(" #n ")" ::: "memory")
; #define PG8_WAIT_L(n) asm volatile("s_waitcnt lgkmcnt(" #n ")" ::: "memory")
; #define PG8_BAR __builtin_amdgcn_s_barrier()
; #define PG8_SCHED __builtin_amdgcn_sched_barrier(0)
; template <class Epi, class Sched>
; __device__ __forceinline__ void gemm_phase(LAS unsigned char* lds, const Gemm g, const Sched& S, const Epi& E) {
;     ...
;             PG8_LDA(At, 1, 1); PG8_STAGE(PG8_SB(1, 0), b3, voffB); PG8_STAGE(PG8_SB(1, 1), b3 + hstepB, voffB); PG8_STAGE(PG8_SA(1, 0), a3, voffA);
;             PG8_WAIT_V(8); PG8_WAIT_L(0); PG8_BAR; PG8_MMA(1, 0, At, B0); PG8_MMA(1, 1, At, B1); PG8_BAR; PG8_SCHED;
;         }
	s_add_i32 s2, s2, s52
	v_lshl_add_u64 v[222:223], v[222:223], 0, s[18:19]
	s_mov_b32 m0, s2
	ds_read_b128 v[188:191], v165 offset:49152
	ds_read_b128 v[192:195], v165 offset:50176
	ds_read_b128 v[196:199], v165 offset:51200
	ds_read_b128 v[200:203], v165 offset:52224
	ds_read_b128 v[204:207], v165 offset:53248
	ds_read_b128 v[210:213], v165 offset:54272
	ds_read_b128 v[214:217], v165 offset:55296
	ds_read_b128 v[218:221], v165 offset:56320
	global_load_lds_dwordx4 v[222:223], off
	s_add_i32 m0, s2, 0x2000
	s_add_u32 s12, s12, 0x80080
	v_lshl_add_u64 v[222:223], v[224:225], 0, s[18:19]
	s_addc_u32 s13, s13, 0
	s_add_i32 s2, s44, s52
	global_load_lds_dwordx4 v[222:223], off
	v_lshl_add_u64 v[222:223], s[12:13], 0, v[130:131]
	s_mov_b32 m0, s2
	s_nop 0
	global_load_lds_dwordx4 v[222:223], off
	v_lshl_add_u64 v[222:223], s[12:13], 0, v[134:135]
	s_add_i32 m0, s2, 0x2000
	s_nop 0
	global_load_lds_dwordx4 v[222:223], off
	v_lshl_add_u64 v[222:223], v[226:227], 0, s[18:19]
	s_mov_b32 m0, s58
	s_nop 0
	global_load_lds_dwordx4 v[222:223], off
	v_lshl_add_u64 v[222:223], v[228:229], 0, s[18:19]
	s_mov_b32 m0, s59
	s_nop 0
	global_load_lds_dwordx4 v[222:223], off
	s_waitcnt vmcnt(8)
	s_waitcnt lgkmcnt(0)
	s_barrier
	s_setprio 1
	s_waitcnt lgkmcnt(0)
	v_mfma_f32_16x16x32_bf16 v[92:95], v[148:151], v[188:191], v[92:95]
	v_mfma_f32_16x16x32_bf16 v[88:91], v[156:159], v[188:191], v[88:91]
	v_mfma_f32_16x16x32_bf16 v[84:87], v[148:151], v[196:199], v[84:87]
	v_mfma_f32_16x16x32_bf16 v[80:83], v[156:159], v[196:199], v[80:83]
	v_mfma_f32_16x16x32_bf16 v[76:79], v[148:151], v[204:207], v[76:79]
	v_mfma_f32_16x16x32_bf16 v[72:75], v[156:159], v[204:207], v[72:75]
	v_mfma_f32_16x16x32_bf16 v[68:71], v[148:151], v[214:217], v[68:71]
	v_mfma_f32_16x16x32_bf16 v[64:67], v[156:159], v[214:217], v[64:67]
	v_mfma_f32_16x16x32_bf16 v[92:95], v[152:155], v[192:195], v[92:95]
	v_mfma_f32_16x16x32_bf16 v[88:91], v[168:171], v[192:195], v[88:91]
	v_mfma_f32_16x16x32_bf16 v[84:87], v[152:155], v[200:203], v[84:87]
	v_mfma_f32_16x16x32_bf16 v[80:83], v[168:171], v[200:203], v[80:83]
	v_mfma_f32_16x16x32_bf16 v[76:79], v[152:155], v[210:213], v[76:79]
	v_mfma_f32_16x16x32_bf16 v[72:75], v[168:171], v[210:213], v[72:75]
	v_mfma_f32_16x16x32_bf16 v[68:71], v[152:155], v[218:221], v[68:71]
	v_mfma_f32_16x16x32_bf16 v[64:67], v[168:171], v[218:221], v[64:67]
	s_setprio 0
	s_setprio 1
	v_mfma_f32_16x16x32_bf16 v[28:31], v[172:175], v[188:191], v[28:31]
	v_mfma_f32_16x16x32_bf16 v[24:27], v[180:183], v[188:191], v[24:27]
	v_mfma_f32_16x16x32_bf16 v[20:23], v[172:175], v[196:199], v[20:23]
	v_mfma_f32_16x16x32_bf16 v[16:19], v[180:183], v[196:199], v[16:19]
	v_mfma_f32_16x16x32_bf16 v[12:15], v[172:175], v[204:207], v[12:15]
	v_mfma_f32_16x16x32_bf16 v[8:11], v[180:183], v[204:207], v[8:11]
	v_mfma_f32_16x16x32_bf16 v[4:7], v[172:175], v[214:217], v[4:7]
	v_mfma_f32_16x16x32_bf16 v[0:3], v[180:183], v[214:217], v[0:3]
	v_mfma_f32_16x16x32_bf16 v[28:31], v[176:179], v[192:195], v[28:31]
	v_mfma_f32_16x16x32_bf16 v[24:27], v[184:187], v[192:195], v[24:27]
	v_mfma_f32_16x16x32_bf16 v[20:23], v[176:179], v[200:203], v[20:23]
	v_mfma_f32_16x16x32_bf16 v[16:19], v[184:187], v[200:203], v[16:19]
	v_mfma_f32_16x16x32_bf16 v[12:15], v[176:179], v[210:213], v[12:15]
	v_mfma_f32_16x16x32_bf16 v[8:11], v[184:187], v[210:213], v[8:11]
	v_mfma_f32_16x16x32_bf16 v[4:7], v[176:179], v[218:221], v[4:7]
	v_mfma_f32_16x16x32_bf16 v[0:3], v[184:187], v[218:221], v[0:3]
	s_setprio 0
	s_barrier
	s_add_i32 s43, s43, 2
	s_add_u32 s8, s8, 0x100
	s_addc_u32 s9, s9, 0
	s_add_u32 s35, s35, 0x100
	s_addc_u32 s42, s42, 0
	s_cmp_gt_u32 s43, 29
	s_cbranch_scc1 .Lwc_exit
	s_cmp_eq_u32 s43, 14
	s_cbranch_scc1 .LBB0_178
	s_branch .Lwc_N
.Lwc_exit:
	s_and_b64 vcc, exec, s[20:21]
	s_cbranch_vccz .LBB0_181
	s_barrier
; #define LAS __attribute__((address_space(3)))
; __device__ __forceinline__ unsigned pk2_rne(float lo, float hi) { const f32x2_t f = {lo, hi}; return __builtin_bit_cast(unsigned, __builtin_convertvector(f, bf16x2_t)); }
; __device__ __forceinline__ float fast_sigmoid(float x) { return __builtin_amdgcn_rcpf(1.0f + __expf(-x)); }
;     __device__ __forceinline__ void operator()(const f32x4 (&acc)[2][2][4][2], const pg8::Unit& u, int wr, int wc, int fr, int fq) const {
;     ...
;         const int type = u.pn >> 2;
;         bf16_t* base = proj + (size_t)type * TSZ;
;         const int row0 = u.pm * 256 + wr * 64 + fr;
;         const int col0 = (u.pn & 3) * 256 + wc * 32 + 8 * fq;
;         const bool rot = (type <= 1) && (wc == 0);
; #pragma unroll
;         for (int bj = 0; bj < 2; ++bj) {
;             float lb[8];
;             if (type == 4) {
;                 const f32x4 a0 = *(const f32x4*)(lbl + col0 + bj * 128), a1 = *(const f32x4*)(lbl + col0 + bj * 128 + 4);
;                 const f32x4 b0 = *(const f32x4*)(lbl + 1024 + col0 + bj * 128), b1 = *(const f32x4*)(lbl + 1024 + col0 + bj * 128 + 4);
; #pragma unroll
;                 for (int e = 0; e < 4; ++e) { lb[e] = fast_sigmoid(a0[e] - b0[e]); lb[4 + e] = fast_sigmoid(a1[e] - b1[e]); }
; __device__ __forceinline__ void transpose_item(const float* __restrict__ W, int K, int N, bf16_t* __restrict__ WT, LAS float* scr, int item, int lane, bool upmap = false) {
;     ...
;         const int n = (lane >> 3) + 8 * j; const LAS float* s = scr + (8 * cch) * 65 + n;
;         u32x4 o; o.x = pk2_rne(s[0], s[65]); o.y = pk2_rne(s[2 * 65], s[3 * 65]); o.z = pk2_rne(s[4 * 65], s[5 * 65]); o.w = pk2_rne(s[6 * 65], s[7 * 65]);
;         *(u32x4*)(WT + (size_t)(n0 + n) * K + k0 + 8 * cch) = o;
.LBB0_181:
	s_lshl_b32 s32, s97, 11
	s_add_i32 s32, s32, 0x20000
	v_lshl_add_u32 v192, v208, 4, s32
	ds_read_b128 v[176:179], v192
	ds_read_b128 v[184:187], v192 offset:1024
	v_lshlrev_b32_e32 v192, 13, v208
	v_add_u32_e32 v193, 0x1000, v192
	s_add_i32 s101, s57, -1
	s_lshl_b32 s101, s101, 11
	s_add_i32 s101, s101, s96
	s_cmp_lg_u32 s94, 0x100
	s_cselect_b32 s101, 0x4000, s101
	s_cmpk_lt_u32 s101, 0x3400
	s_cbranch_scc0 .Lwc_nostore
	s_and_b32 s32, s101, 0x7f
	s_lshl_b32 s32, s32, 5
	s_cmpk_lt_u32 s101, 0x2c00
	s_cbranch_scc0 .Lwc_dst_out
	s_lshr_b32 s100, s101, 7
	s_cmp_lt_u32 s100, 44
	s_cbranch_scc1 .Lwc_up_lo
	s_sub_i32 s100, s100, 44
	s_lshl_b32 s100, s100, 8
	s_add_i32 s100, s100, 0x80
	s_branch .Lwc_up_j
.Lwc_up_lo:
	s_lshl_b32 s100, s100, 8
.Lwc_up_j:
	s_lshl_b32 s100, s100, 12
	s_add_i32 s100, s100, 0x1700000
	s_branch .Lwc_dst_j
.Lwc_dst_out:
	s_sub_i32 s100, s101, 0x2c00
	s_lshr_b32 s100, s100, 7
	s_lshl_b32 s100, s100, 19
	s_add_i32 s100, s100, 0x6f00000
.Lwc_dst_j:
	s_add_i32 s100, s100, s32
	s_add_u32 s100, s100, s90
	s_addc_u32 s101, s91, 0
	s_waitcnt lgkmcnt(0)
	global_store_dwordx4 v192, v[176:179], s[100:101]
	global_store_dwordx4 v192, v[232:235], s[100:101] offset:16
	global_store_dwordx4 v193, v[184:187], s[100:101]
	global_store_dwordx4 v193, v[236:239], s[100:101] offset:16
.Lwc_nostore:
	s_waitcnt lgkmcnt(0)
	s_lshl_b32 s2, s6, 8
	s_ashr_i32 s12, s6, 2
	s_and_b32 s2, s2, 0x300
	s_cmp_eq_u32 s12, 4
	s_nop 7
	s_nop 7
	s_nop 7
	s_cselect_b64 s[44:45], -1, 0
	s_cmp_lg_u32 s12, 4
	v_or_b32_e32 v136, s2, v162
	s_cselect_b64 s[40:41], -1, 0
	v_mov_b32_e32 v174, 0
	s_and_b64 vcc, exec, s[40:41]
	v_lshlrev_b32_e32 v148, 2, v136
	v_mov_b32_e32 v173, 0
	v_mov_b32_e32 v172, 0
	v_mov_b32_e32 v171, 0
	v_mov_b32_e32 v170, 0
	v_mov_b32_e32 v169, 0
	v_mov_b32_e32 v168, 0
	v_mov_b32_e32 v149, 0
	s_cbranch_vccnz .LBB0_183
	v_readlane_b32 s72, v245, 31
	v_readlane_b32 s86, v245, 45
	v_readlane_b32 s87, v245, 46
	s_nop 4
	global_load_dwordx4 v[150:153], v148, s[86:87] offset:16
	global_load_dwordx4 v[154:157], v148, s[86:87]
	global_load_dwordx4 v[168:171], v148, s[22:23]
	global_load_dwordx4 v[172:175], v148, s[22:23] offset:16
	v_readlane_b32 s73, v245, 32
	v_readlane_b32 s74, v245, 33
	v_readlane_b32 s75, v245, 34
	v_readlane_b32 s76, v245, 35
	v_readlane_b32 s77, v245, 36
	v_readlane_b32 s78, v245, 37
	v_readlane_b32 s79, v245, 38
	v_readlane_b32 s80, v245, 39
	v_readlane_b32 s81, v245, 40
	v_readlane_b32 s82, v245, 41
	v_readlane_b32 s83, v245, 42
	v_readlane_b32 s84, v245, 43
	v_readlane_b32 s85, v245, 44
	s_waitcnt vmcnt(0)
	v_sub_f32_e32 v149, v154, v168
	v_sub_f32_e32 v150, v150, v172
	v_sub_f32_e32 v154, v155, v169
	v_sub_f32_e32 v151, v151, v173
	v_sub_f32_e32 v155, v156, v170
	v_sub_f32_e32 v152, v152, v174
	v_sub_f32_e32 v156, v157, v171
	v_sub_f32_e32 v153, v153, v175
	v_mul_f32_e32 v149, 0xbfb8aa3b, v149
	v_mul_f32_e32 v150, 0xbfb8aa3b, v150
	v_mul_f32_e32 v154, 0xbfb8aa3b, v154
	v_mul_f32_e32 v151, 0xbfb8aa3b, v151
	v_mul_f32_e32 v155, 0xbfb8aa3b, v155
	v_mul_f32_e32 v152, 0xbfb8aa3b, v152
	v_mul_f32_e32 v156, 0xbfb8aa3b, v156
	v_mul_f32_e32 v153, 0xbfb8aa3b, v153
	v_exp_f32_e32 v149, v149
	v_exp_f32_e32 v150, v150
	v_exp_f32_e32 v154, v154
	v_exp_f32_e32 v151, v151
	v_exp_f32_e32 v155, v155
	v_exp_f32_e32 v152, v152
	v_exp_f32_e32 v156, v156
	v_exp_f32_e32 v153, v153
	v_add_f32_e32 v149, 1.0, v149
	v_add_f32_e32 v150, 1.0, v150
	v_add_f32_e32 v154, 1.0, v154
	v_add_f32_e32 v151, 1.0, v151
	v_add_f32_e32 v155, 1.0, v155
	v_add_f32_e32 v152, 1.0, v152
	v_add_f32_e32 v156, 1.0, v156
	v_add_f32_e32 v153, 1.0, v153
	v_rcp_f32_e32 v174, v149
	v_rcp_f32_e32 v170, v150
	v_rcp_f32_e32 v173, v154
	v_rcp_f32_e32 v169, v151
	v_rcp_f32_e32 v172, v155
	v_rcp_f32_e32 v168, v152
	v_rcp_f32_e32 v171, v156
	v_rcp_f32_e32 v149, v153

; #define LAS __attribute__((address_space(3)))
; __global__ void __launch_bounds__(512, 2) fwd_mega(Args a) {
;     extern __shared__ __attribute__((aligned(16))) unsigned char lds_raw[];
;     cg::grid_group grid = cg::this_grid();
;     Ctx X;
;     X.lds = (LAS unsigned char*)lds_raw; X.ws = a.ws; X.out = a.out;
;     X.x = (const float*)a.in[0]; X.c = (const float*)a.in[1]; X.pos = (const int*)a.in[2]; X.w_ada = (const float*)a.in[3]; X.b_ada = (const float*)a.in[4];
;     X.norm1_w = (const float*)a.in[5]; X.w_in = (const float*)a.in[6]; X.lb_logits = (const float*)a.in[7]; X.gnorm_w = (const float*)a.in[8]; X.w_out = (const float*)a.in[9];
;     X.norm2_w = (const float*)a.in[10]; X.w_up = (const float*)a.in[11]; X.conv_w = (const float*)a.in[12]; X.conv_b = (const float*)a.in[13]; X.w_down = (const float*)a.in[14]; X.final_w = (const float*)a.in[15];
;     X.tid = threadIdx.x; X.lane = X.tid & 63; X.wave = __builtin_amdgcn_readfirstlane(X.tid >> 6); X.G = gridDim.x;
;     X.gw = blockIdx.x * NWAVES + X.wave; X.NGW = X.G * NWAVES;
	.amdhsa_kernel _Z8fwd_mega4Args
		.amdhsa_group_segment_fixed_size 0
		.amdhsa_private_segment_fixed_size 0
		.amdhsa_kernarg_size 408
		.amdhsa_user_sgpr_count 2
		.amdhsa_user_sgpr_dispatch_ptr 0
		.amdhsa_user_sgpr_queue_ptr 0
		.amdhsa_user_sgpr_kernarg_segment_ptr 1
		.amdhsa_user_sgpr_dispatch_id 0
		.amdhsa_user_sgpr_kernarg_preload_length 0
		.amdhsa_user_sgpr_kernarg_preload_offset 0
		.amdhsa_user_sgpr_private_segment_size 0
		.amdhsa_uses_dynamic_stack 0
		.amdhsa_enable_private_segment 0
		.amdhsa_system_sgpr_workgroup_id_x 1
		.amdhsa_system_sgpr_workgroup_id_y 0
		.amdhsa_system_sgpr_workgroup_id_z 0
		.amdhsa_system_sgpr_workgroup_info 0
		.amdhsa_system_vgpr_workitem_id 2
		.amdhsa_next_free_vgpr 256
		.amdhsa_next_free_sgpr 102
		.amdhsa_accum_offset 248
		.amdhsa_reserve_vcc 1
		.amdhsa_float_round_mode_32 0
		.amdhsa_float_round_mode_16_64 0
		.amdhsa_float_denorm_mode_32 3
		.amdhsa_float_denorm_mode_16_64 3
		.amdhsa_dx10_clamp 1
		.amdhsa_ieee_mode 1
		.amdhsa_fp16_overflow 0
		.amdhsa_tg_split 0
		.amdhsa_exception_fp_ieee_invalid_op 0
		.amdhsa_exception_fp_denorm_src 0
		.amdhsa_exception_fp_ieee_div_zero 0
		.amdhsa_exception_fp_ieee_overflow 0
		.amdhsa_exception_fp_ieee_underflow 0
		.amdhsa_exception_fp_ieee_inexact 0
		.amdhsa_exception_int_div_zero 0
	.end_amdhsa_kernel

; #define LAS __attribute__((address_space(3)))
; __global__ void __launch_bounds__(512, 2) fwd_mega(Args a) {
;     extern __shared__ __attribute__((aligned(16))) unsigned char lds_raw[];
;     cg::grid_group grid = cg::this_grid();
;     Ctx X;
;     X.lds = (LAS unsigned char*)lds_raw; X.ws = a.ws; X.out = a.out;
;     X.x = (const float*)a.in[0]; X.c = (const float*)a.in[1]; X.pos = (const int*)a.in[2]; X.w_ada = (const float*)a.in[3]; X.b_ada = (const float*)a.in[4];
;     X.norm1_w = (const float*)a.in[5]; X.w_in = (const float*)a.in[6]; X.lb_logits = (const float*)a.in[7]; X.gnorm_w = (const float*)a.in[8]; X.w_out = (const float*)a.in[9];
;     X.norm2_w = (const float*)a.in[10]; X.w_up = (const float*)a.in[11]; X.conv_w = (const float*)a.in[12]; X.conv_b = (const float*)a.in[13]; X.w_down = (const float*)a.in[14]; X.final_w = (const float*)a.in[15];
;     X.tid = threadIdx.x; X.lane = X.tid & 63; X.wave = __builtin_amdgcn_readfirstlane(X.tid >> 6); X.G = gridDim.x;
;     X.gw = blockIdx.x * NWAVES + X.wave; X.NGW = X.G * NWAVES;
amdhsa.kernels:
  - .agpr_count:     8
    .args:
      - .offset:         0
        .size:           152
        .value_kind:     by_value
      - .offset:         152
        .size:           4
        .value_kind:     hidden_block_count_x
      - .offset:         156
        .size:           4
        .value_kind:     hidden_block_count_y
      - .offset:         160
        .size:           4
        .value_kind:     hidden_block_count_z
      - .offset:         164
        .size:           2
        .value_kind:     hidden_group_size_x
      - .offset:         166
        .size:           2
        .value_kind:     hidden_group_size_y
      - .offset:         168
        .size:           2
        .value_kind:     hidden_group_size_z
      - .offset:         170
        .size:           2
        .value_kind:     hidden_remainder_x
      - .offset:         172
        .size:           2
        .value_kind:     hidden_remainder_y
      - .offset:         174
        .size:           2
        .value_kind:     hidden_remainder_z
      - .offset:         192
        .size:           8
        .value_kind:     hidden_global_offset_x
      - .offset:         200
        .size:           8
        .value_kind:     hidden_global_offset_y
      - .offset:         208
        .size:           8
        .value_kind:     hidden_global_offset_z
      - .offset:         216
        .size:           2
        .value_kind:     hidden_grid_dims
      - .offset:         240
        .size:           8
        .value_kind:     hidden_multigrid_sync_arg
      - .offset:         272
        .size:           4
        .value_kind:     hidden_dynamic_lds_size
    .group_segment_fixed_size: 0
    .kernarg_segment_align: 8
    .kernarg_segment_size: 408
    .language:       OpenCL C
    .language_version:
      - 2
      - 0
    .max_flat_workgroup_size: 512
    .name:           _Z8fwd_mega4Args
    .private_segment_fixed_size: 0
    .sgpr_count:     108
    .sgpr_spill_count: 84
    .symbol:         _Z8fwd_mega4Args.kd
    .uniform_work_group_size: 1
    .uses_dynamic_stack: false
    .vgpr_count:     256
    .vgpr_spill_count: 0
    .wavefront_size: 64
